# attention P.V hoist with three MFMAs per step in the pack tail (v63 otherwise)
# baseline (speedup 1.0000x reference)
.LBB0_999:
	v_mfma_f32_32x32x16_bf16 v[20:35], v[80:83], v[164:167], v[20:35]
	global_load_lds_dwordx4 v190, s[48:49]
	s_cselect_b32 s49, s49, s51
	s_cselect_b32 s48, s48, s50
	s_cselect_b32 s43, s38, s40
	s_add_i32 m0, s21, s43
	s_add_i32 s43, s23, s40
	global_load_lds_dwordx4 v192, s[48:49]
	s_add_i32 m0, s43, 0xd000
	s_mov_b32 s43, s39
	global_load_lds_dwordx4 v194, s[50:51]
	s_mov_b32 s39, s44
	s_mov_b32 s44, s15
	s_mov_b32 s45, s14
	v_max3_f32 v2, v52, v36, v53
	s_nop 0
	v_max3_f32 v2, v2, v37, v54
	s_nop 0
	v_mfma_f32_32x32x16_bf16 v[4:19], v[76:79], v[176:179], v[4:19]
	v_max3_f32 v2, v2, v38, v55
	s_nop 0
	v_max3_f32 v2, v2, v39, v56
	v_max3_f32 v68, v60, v44, v61
	v_max3_f32 v2, v2, v40, v57
	s_nop 0
	v_max3_f32 v68, v68, v45, v62
	v_mfma_f32_32x32x16_bf16 v[20:35], v[76:79], v[156:159], v[20:35]
	v_max3_f32 v2, v2, v41, v58
	s_nop 0
	v_max3_f32 v68, v68, v46, v63
	v_max3_f32 v68, v68, v47, v64
	v_max3_f32 v2, v2, v42, v59
	v_max3_f32 v68, v68, v48, v65
	s_nop 0
	v_mfma_f32_32x32x16_bf16 v[20:35], v[72:75], v[152:155], v[20:35]
	v_max3_f32 v68, v68, v49, v66
	v_max3_f32 v68, v68, v50, v67
	s_nop 0
	v_max3_f32 v2, v2, v43, v68
	s_nop 0
	v_max3_f32 v2, v2, v51, v2
	s_nop 0
	v_mfma_f32_32x32x16_bf16 v[4:19], v[72:75], v[148:151], v[4:19]
	v_mov_b32_e32 v69, v2
	s_nop 1
	v_permlane32_swap_b32_e32 v2, v69
	v_max3_f32 v2, v2, v69, v2
	s_nop 0
	v_cmp_lt_f32_e32 vcc, s56, v2
	s_cbranch_vccz .LBB0_1003
	v_add_f32_e32 v180, v210, v2
	v_cvt_pk_bf16_f32 v180, v180, v180
	v_lshlrev_b32_e32 v180, 16, v180
	v_cndmask_b32_e32 v180, v210, v180, vcc
	v_sub_f32_e32 v2, v210, v180
	v_sub_f32_e32 v84, v180, v210
	v_xor_b32_e32 v250, 0x80000000, v180
	v_min_f32_e32 v2, 0, v2
	v_lshrrev_b32_e32 v250, 16, v250
	v_exp_f32_e32 v2, v2
	v_cndmask_b32_e64 v250, 0, v250, s[2:3]
	s_and_saveexec_b64 s[14:15], s[2:3]
	ds_write_b32 v202, v2
	s_or_b64 exec, exec, s[14:15]
	ds_read_b32 v68, v1
	ds_read_b32 v69, v1 offset:4
	ds_read_b32 v70, v1 offset:8
	ds_read_b32 v71, v1 offset:12
	ds_read_b32 v72, v1 offset:32
	ds_read_b32 v73, v1 offset:36
	ds_read_b32 v74, v1 offset:40
	ds_read_b32 v75, v1 offset:44
	ds_read_b32 v76, v1 offset:64
	ds_read_b32 v77, v1 offset:68
	ds_read_b32 v78, v1 offset:72
	ds_read_b32 v79, v1 offset:76
	ds_read_b32 v80, v1 offset:96
	ds_read_b32 v81, v1 offset:100
	ds_read_b32 v82, v1 offset:104
	ds_read_b32 v83, v1 offset:108
	v_mul_f32_e32 v209, v209, v2
	s_waitcnt lgkmcnt(0)
	v_pk_mul_f32 v[20:21], v[20:21], v[68:69]
	v_pk_mul_f32 v[22:23], v[22:23], v[70:71]
	v_pk_mul_f32 v[24:25], v[24:25], v[72:73]
	v_pk_mul_f32 v[26:27], v[26:27], v[74:75]
	v_pk_mul_f32 v[28:29], v[28:29], v[76:77]
	v_pk_mul_f32 v[30:31], v[30:31], v[78:79]
	v_pk_mul_f32 v[32:33], v[32:33], v[80:81]
	v_pk_mul_f32 v[34:35], v[34:35], v[82:83]
	v_pk_mul_f32 v[4:5], v[4:5], v[68:69]
	v_pk_mul_f32 v[6:7], v[6:7], v[70:71]
	v_pk_mul_f32 v[8:9], v[8:9], v[72:73]
	v_pk_mul_f32 v[10:11], v[10:11], v[74:75]
	v_pk_mul_f32 v[12:13], v[12:13], v[76:77]
	v_pk_mul_f32 v[14:15], v[14:15], v[78:79]
	v_pk_mul_f32 v[16:17], v[16:17], v[80:81]
	v_pk_mul_f32 v[18:19], v[18:19], v[82:83]
	v_sub_f32_e32 v36, v36, v84
	v_sub_f32_e32 v37, v37, v84
	v_sub_f32_e32 v38, v38, v84
	v_sub_f32_e32 v39, v39, v84
	v_sub_f32_e32 v40, v40, v84
	v_sub_f32_e32 v41, v41, v84
	v_sub_f32_e32 v42, v42, v84
	v_sub_f32_e32 v43, v43, v84
	v_sub_f32_e32 v44, v44, v84
	v_sub_f32_e32 v45, v45, v84
	v_sub_f32_e32 v46, v46, v84
	v_sub_f32_e32 v47, v47, v84
	v_sub_f32_e32 v48, v48, v84
	v_sub_f32_e32 v49, v49, v84
	v_sub_f32_e32 v50, v50, v84
	v_sub_f32_e32 v51, v51, v84
	v_sub_f32_e32 v52, v52, v84
	v_sub_f32_e32 v53, v53, v84
	v_sub_f32_e32 v54, v54, v84
	v_sub_f32_e32 v55, v55, v84
	v_sub_f32_e32 v56, v56, v84
	v_sub_f32_e32 v57, v57, v84
	v_sub_f32_e32 v58, v58, v84
	v_sub_f32_e32 v59, v59, v84
	v_sub_f32_e32 v60, v60, v84
	v_sub_f32_e32 v61, v61, v84
	v_sub_f32_e32 v62, v62, v84
	v_sub_f32_e32 v63, v63, v84
	v_sub_f32_e32 v64, v64, v84
	v_sub_f32_e32 v65, v65, v84
	v_sub_f32_e32 v66, v66, v84
	v_sub_f32_e32 v67, v67, v84
	s_mov_b32 s56, 0x41000000
	s_branch .LBB0_1004

.LBB0_1004:
	v_mfma_f32_32x32x16_bf16 v[68:83], v[246:249], v[250:253], 0
	v_mfma_f32_32x32x16_bf16 v[84:99], v[132:135], v[100:103], v[68:83]
	v_mfma_f32_32x32x16_bf16 v[68:83], v[136:139], v[100:103], v[68:83]
	v_add_u32_e32 v2, s45, v189
	ds_read_b128 v[184:187], v2 offset:96
	ds_read_b128 v[210:213], v2 offset:128
	ds_read_b128 v[214:217], v2 offset:6752
	ds_read_b128 v[218:221], v2 offset:160
	ds_read_b128 v[222:225], v2 offset:6784
	ds_read_b128 v[226:229], v2 offset:6816
	v_add_u32_e32 v2, s39, v200
	ds_read_b128 v[176:179], v2 offset:53248
	ds_read_b128 v[164:167], v2 offset:53280
	ds_read_b128 v[230:233], v2 offset:57856
	ds_read_b128 v[238:241], v2 offset:57888
	ds_read_b128 v[160:163], v2 offset:53312
	ds_read_b128 v[156:159], v2 offset:53344
	ds_read_b128 v[242:245], v2 offset:57920
	ds_read_b128 v[152:155], v2 offset:57952
	v_exp_f32_e32 v52, v52
	v_exp_f32_e32 v183, v36
	v_exp_f32_e32 v132, v53
	v_exp_f32_e32 v53, v54
	v_mfma_f32_32x32x16_bf16 v[68:83], v[144:147], v[104:107], v[68:83]
	v_exp_f32_e32 v54, v38
	v_exp_f32_e32 v36, v55
	v_exp_f32_e32 v55, v56
	v_exp_f32_e32 v56, v40
	v_mfma_f32_32x32x16_bf16 v[84:99], v[128:131], v[104:107], v[84:99]
	v_exp_f32_e32 v40, v39
	v_exp_f32_e32 v38, v57
	v_exp_f32_e32 v57, v58
	v_exp_f32_e32 v58, v41
	v_mfma_f32_32x32x16_bf16 v[68:83], v[140:143], v[108:111], v[68:83]
	v_add_u32_e32 v181, s44, v189
	ds_read_b128 v[144:147], v181
	ds_read_b128 v[172:175], v181 offset:32
	ds_read_b128 v[136:139], v181 offset:6656
	ds_read_b128 v[168:171], v181 offset:64
	ds_read_b128 v[148:151], v181 offset:6688
	ds_read_b128 v[140:143], v181 offset:6720
	v_exp_f32_e32 v2, v37
	v_mfma_f32_32x32x16_bf16 v[84:99], v[124:127], v[108:111], v[84:99]
	v_exp_f32_e32 v124, v59
	v_exp_f32_e32 v41, v60
	v_add_f32_e32 v133, v52, v183
	v_add_f32_e32 v37, v53, v54
	s_waitcnt lgkmcnt(14)
	v_mfma_f32_32x32x16_bf16 v[68:83], v[214:217], v[112:115], v[68:83]
	v_exp_f32_e32 v214, v42
	v_exp_f32_e32 v59, v44
	v_exp_f32_e32 v60, v43
	v_exp_f32_e32 v126, v61
	v_mfma_f32_32x32x16_bf16 v[84:99], v[184:187], v[112:115], v[84:99]
	v_exp_f32_e32 v61, v62
	v_exp_f32_e32 v62, v45
	v_exp_f32_e32 v128, v63
	v_exp_f32_e32 v63, v64
	v_mfma_f32_32x32x16_bf16 v[68:83], v[222:225], v[116:119], v[68:83]
	v_exp_f32_e32 v216, v48
	v_exp_f32_e32 v64, v47
	v_exp_f32_e32 v130, v65
	v_mfma_f32_32x32x16_bf16 v[84:99], v[210:213], v[116:119], v[84:99]
	v_exp_f32_e32 v65, v66
	v_exp_f32_e32 v215, v46
	v_exp_f32_e32 v185, v50
	v_mfma_f32_32x32x16_bf16 v[68:83], v[226:229], v[120:123], v[68:83]
	v_exp_f32_e32 v66, v49
	v_exp_f32_e32 v134, v67
	v_add_f32_e32 v39, v55, v56
	v_add_f32_e32 v125, v57, v214
	v_mfma_f32_32x32x16_bf16 v[84:99], v[218:221], v[120:123], v[84:99]
	v_add_f32_e32 v127, v41, v59
	v_add_f32_e32 v129, v61, v215
	v_add_f32_e32 v131, v63, v216
	v_add_f32_e32 v135, v65, v185
	v_exp_f32_e32 v184, v51
	v_cvt_pk_bf16_f32 v42, v52, v132
	v_cvt_pk_bf16_f32 v43, v53, v36
	v_cvt_pk_bf16_f32 v44, v55, v38
	v_cvt_pk_bf16_f32 v45, v57, v124
	v_cvt_pk_bf16_f32 v46, v41, v126
	v_cvt_pk_bf16_f32 v47, v61, v128
	s_waitcnt lgkmcnt(10)
	v_mfma_f32_32x32x16_bf16 v[4:19], v[42:45], v[230:233], v[4:19]
	v_cvt_pk_bf16_f32 v48, v63, v130
	v_cvt_pk_bf16_f32 v49, v65, v134
	v_cvt_pk_bf16_f32 v50, v183, v2
	v_cvt_pk_bf16_f32 v51, v54, v40
	v_mfma_f32_32x32x16_bf16 v[20:35], v[42:45], v[176:179], v[20:35]
	v_cvt_pk_bf16_f32 v52, v56, v58
	v_cvt_pk_bf16_f32 v53, v214, v60
	v_cvt_pk_bf16_f32 v54, v59, v62
	v_cvt_pk_bf16_f32 v55, v215, v64
	v_mfma_f32_32x32x16_bf16 v[4:19], v[46:49], v[238:241], v[4:19]
	v_cvt_pk_bf16_f32 v56, v216, v66
	v_cvt_pk_bf16_f32 v57, v185, v184
	s_add_i32 s14, s46, 5
	s_min_u32 s14, s14, s37
	s_add_i32 s15, s46, 3
	s_min_u32 s46, s15, s37
	s_mulk_i32 s14, 0x3000
	s_add_u32 s14, s10, s14
	s_addc_u32 s15, s11, 0
	s_lshl_b32 s46, s46, 13
	s_add_u32 s46, s12, s46
	s_addc_u32 s47, s13, 0
	s_add_i32 m0, s22, s45
	s_and_b64 s[48:49], s[4:5], exec
	s_waitcnt vmcnt(3) lgkmcnt(0)
	s_barrier
	v_mfma_f32_32x32x16_bf16 v[20:35], v[46:49], v[164:167], v[20:35]
	global_load_lds_dwordx4 v190, s[14:15]
	s_cselect_b32 s15, s15, s47
	s_cselect_b32 s14, s14, s46
	s_cselect_b32 s98, s45, s39
	s_add_i32 m0, s21, s98
	s_add_i32 s98, s23, s39
	global_load_lds_dwordx4 v192, s[14:15]
	s_add_i32 m0, s98, 0xd000
	s_nop 0
	global_load_lds_dwordx4 v194, s[46:47]
	v_max3_f32 v41, v84, v68, v85
	v_max3_f32 v59, v92, v76, v93
	v_add_f32_e32 v132, v132, v2
	v_max3_f32 v41, v41, v69, v86
	v_max3_f32 v59, v59, v77, v94
	s_nop 0
	v_max3_f32 v41, v41, v70, v87
	v_mfma_f32_32x32x16_bf16 v[4:19], v[50:53], v[242:245], v[4:19]
	v_max3_f32 v41, v41, v71, v88
	v_max3_f32 v59, v59, v78, v95
	v_max3_f32 v41, v41, v72, v89
	v_max3_f32 v59, v59, v79, v96
	s_nop 0
	v_max3_f32 v41, v41, v73, v90
	v_max3_f32 v183, v41, v74, v91
	v_add_f32_e32 v41, v132, v133
	v_max3_f32 v59, v59, v80, v97
	v_add_f32_e64 v36, v36, v40
	v_add_f32_e64 v37, v37, v41
	v_mfma_f32_32x32x16_bf16 v[20:35], v[50:53], v[160:163], v[20:35]
	v_max3_f32 v59, v59, v81, v98
	v_max3_f32 v186, v59, v82, v99
	v_add_f32_e32 v59, v36, v37
	v_add_f32_e32 v36, v38, v58
	v_add_f32_e32 v37, v39, v59
	v_add_f32_e32 v61, v36, v37
	v_add_f32_e32 v36, v124, v60
	v_add_f32_e32 v37, v125, v61
	v_add_f32_e32 v63, v36, v37
	v_add_f32_e32 v36, v126, v62
	v_add_f32_e32 v37, v127, v63
	v_mfma_f32_32x32x16_bf16 v[20:35], v[54:57], v[156:159], v[20:35]
	v_add_f32_e32 v65, v36, v37
	v_add_f32_e32 v36, v128, v64
	v_add_f32_e32 v37, v129, v65
	v_add_f32_e32 v67, v36, v37
	v_add_f32_e32 v36, v130, v66
	v_add_f32_e32 v37, v131, v67
	v_add_f32_e32 v185, v36, v37
	v_add_f32_e32 v36, v134, v184
	v_add_f32_e32 v37, v135, v185
	v_add_f32_e32 v2, v36, v37
	v_max3_f32 v36, v183, v75, v186
	v_mfma_f32_32x32x16_bf16 v[4:19], v[54:57], v[152:155], v[4:19]
	v_add_f32_e32 v2, v209, v2
	v_max3_f32 v36, v36, v83, v36
	s_nop 0
	v_mov_b32_e32 v38, v36
	s_nop 0
	s_nop 0
	v_permlane32_swap_b32_e32 v36, v38
	v_max3_f32 v36, v36, v38, v36
	s_nop 0
	v_cmp_lt_f32_e32 vcc, s56, v36
	s_cbranch_vccz .LBB0_1008
	s_nop 0
	v_add_f32_e32 v210, v180, v36
	v_cvt_pk_bf16_f32 v210, v210, v210
	v_lshlrev_b32_e32 v210, 16, v210
	v_cndmask_b32_e32 v210, v180, v210, vcc
	v_sub_f32_e32 v36, v180, v210
	v_sub_f32_e32 v186, v210, v180
	v_xor_b32_e32 v250, 0x80000000, v210
	v_min_f32_e32 v36, 0, v36
	v_lshrrev_b32_e32 v250, 16, v250
	v_exp_f32_e32 v36, v36
	v_cndmask_b32_e64 v250, 0, v250, s[2:3]
	s_and_saveexec_b64 s[14:15], s[2:3]
	ds_write_b32 v202, v36
	s_or_b64 exec, exec, s[14:15]
	v_mul_f32_e32 v2, v2, v36
	ds_read_b32 v36, v1
	ds_read_b32 v37, v1 offset:4
	ds_read_b32 v38, v1 offset:8
	ds_read_b32 v39, v1 offset:12
	ds_read_b32 v40, v1 offset:32
	ds_read_b32 v41, v1 offset:36
	ds_read_b32 v42, v1 offset:40
	ds_read_b32 v43, v1 offset:44
	ds_read_b32 v44, v1 offset:64
	ds_read_b32 v45, v1 offset:68
	ds_read_b32 v46, v1 offset:72
	ds_read_b32 v47, v1 offset:76
	ds_read_b32 v48, v1 offset:96
	ds_read_b32 v49, v1 offset:100
	ds_read_b32 v50, v1 offset:104
	ds_read_b32 v51, v1 offset:108
	s_waitcnt lgkmcnt(0)
	v_pk_mul_f32 v[20:21], v[20:21], v[36:37]
	v_pk_mul_f32 v[22:23], v[22:23], v[38:39]
	v_pk_mul_f32 v[24:25], v[24:25], v[40:41]
	v_pk_mul_f32 v[26:27], v[26:27], v[42:43]
	v_pk_mul_f32 v[28:29], v[28:29], v[44:45]
	v_pk_mul_f32 v[30:31], v[30:31], v[46:47]
	v_pk_mul_f32 v[32:33], v[32:33], v[48:49]
	v_pk_mul_f32 v[34:35], v[34:35], v[50:51]
	v_pk_mul_f32 v[4:5], v[4:5], v[36:37]
	v_pk_mul_f32 v[6:7], v[6:7], v[38:39]
	v_pk_mul_f32 v[8:9], v[8:9], v[40:41]
	v_pk_mul_f32 v[10:11], v[10:11], v[42:43]
	v_pk_mul_f32 v[12:13], v[12:13], v[44:45]
	v_pk_mul_f32 v[14:15], v[14:15], v[46:47]
	v_pk_mul_f32 v[16:17], v[16:17], v[48:49]
	v_pk_mul_f32 v[18:19], v[18:19], v[50:51]
	v_sub_f32_e32 v68, v68, v186
	v_sub_f32_e32 v69, v69, v186
	v_sub_f32_e32 v70, v70, v186
	v_sub_f32_e32 v71, v71, v186
	v_sub_f32_e32 v72, v72, v186
	v_sub_f32_e32 v73, v73, v186
	v_sub_f32_e32 v74, v74, v186
	v_sub_f32_e32 v75, v75, v186
	v_sub_f32_e32 v76, v76, v186
	v_sub_f32_e32 v77, v77, v186
	v_sub_f32_e32 v78, v78, v186
	v_sub_f32_e32 v79, v79, v186
	v_sub_f32_e32 v80, v80, v186
	v_sub_f32_e32 v81, v81, v186
	v_sub_f32_e32 v82, v82, v186
	v_sub_f32_e32 v83, v83, v186
	v_sub_f32_e32 v84, v84, v186
	v_sub_f32_e32 v85, v85, v186
	v_sub_f32_e32 v86, v86, v186
	v_sub_f32_e32 v87, v87, v186
	v_sub_f32_e32 v88, v88, v186
	v_sub_f32_e32 v89, v89, v186
	v_sub_f32_e32 v90, v90, v186
	v_sub_f32_e32 v91, v91, v186
	v_sub_f32_e32 v92, v92, v186
	v_sub_f32_e32 v93, v93, v186
	v_sub_f32_e32 v94, v94, v186
	v_sub_f32_e32 v95, v95, v186
	v_sub_f32_e32 v96, v96, v186
	v_sub_f32_e32 v97, v97, v186
	v_sub_f32_e32 v98, v98, v186
	v_sub_f32_e32 v99, v99, v186
	s_mov_b32 s56, 0x41000000
	s_branch .LBB0_1009

; #define AT_KRD(dst, koff, ks0) do { const LAS unsigned char* Kl = Kr + (koff); \
;             _Pragma("unroll") for (int ks = 0; ks < 3; ++ks) { dst[2 * ks] = *(const LAS bf16x8_t*)(Kl + ((ks0) + ks) * 32); dst[2 * ks + 1] = *(const LAS bf16x8_t*)(Kl + 32 * AT_KP + ((ks0) + ks) * 32); } } while (0)
; #define AT_KMM(P0, P1, src, ks0) do { _Pragma("unroll") for (int ks = 0; ks < 3; ++ks) { \
;             P0 = __builtin_amdgcn_mfma_f32_32x32x16_bf16(src[2 * ks], qf[(ks0) + ks], P0, 0, 0, 0); P1 = __builtin_amdgcn_mfma_f32_32x32x16_bf16(src[2 * ks + 1], qf[(ks0) + ks], P1, 0, 0, 0); } } while (0)
; #define AT_ZERO(P0, P1) do { _Pragma("unroll") for (int r = 0; r < 16; ++r) { P0[r] = 0.f; P1[r] = 0.f; } } while (0)
; __device__ __forceinline__ void ph_attn(Frame& F) {
;     ...
;         int kq = AT_KB, kn = 2 * AT_KB, k3 = 3 * AT_KB, kw = 0, vn = 0, v1 = AT_VB, vw = 2 * AT_VB;
;         { bf16x8_t kg[6]; AT_KRD(kf, 0, 0); AT_KRD(kg, 0, 3); AT_ZERO(pA0, pA1); AT_KMM(pA0, pA1, kf, 0); AT_KMM(pA0, pA1, kg, 3); AT_KRD(kf, AT_KB, 0); }
;         __syncthreads();
;         if (AT_PRIO && __builtin_amdgcn_readfirstlane(wave) >= 4) __builtin_amdgcn_s_setprio(1);
;         for (int t = 0; t < NT; t += 2) {
;             AT_STEP(pA0, pA1, pB0, pB1, t);
;             AT_STEP(pB0, pB1, pA0, pA1, t + 1);
;         }
.LBB0_1009:
	v_mfma_f32_32x32x16_bf16 v[36:51], v[246:249], v[250:253], 0
	v_mfma_f32_32x32x16_bf16 v[52:67], v[144:147], v[100:103], v[36:51]
	v_mfma_f32_32x32x16_bf16 v[36:51], v[136:139], v[100:103], v[36:51]
	v_add_u32_e32 v255, s43, v200
	ds_read_b128 v[212:215], v181 offset:96
	ds_read_b128 v[216:219], v181 offset:128
	ds_read_b128 v[220:223], v181 offset:6752
	ds_read_b128 v[224:227], v181 offset:160
	ds_read_b128 v[228:231], v181 offset:6784
	ds_read_b128 v[238:241], v181 offset:6816
	ds_read_b128 v[160:163], v255 offset:53248
	ds_read_b128 v[164:167], v255 offset:53280
	ds_read_b128 v[184:187], v255 offset:57856
	ds_read_b128 v[180:183], v255 offset:57888
	ds_read_b128 v[156:159], v255 offset:53312
	ds_read_b128 v[152:155], v255 offset:53344
	v_add_u32_e32 v209, s41, v189
	v_mfma_f32_32x32x16_bf16 v[36:51], v[148:151], v[104:107], v[36:51]
	ds_read_b128 v[176:179], v255 offset:57920
	ds_read_b128 v[148:151], v255 offset:57952
	v_exp_f32_e32 v211, v84
	v_exp_f32_e32 v232, v68
	v_exp_f32_e32 v233, v85
	v_exp_f32_e32 v235, v69
	v_add_f32_e32 v68, v211, v232
	v_add_f32_e32 v69, v233, v235
	v_add_f32_e32 v68, v69, v68
	v_mfma_f32_32x32x16_bf16 v[52:67], v[172:175], v[104:107], v[52:67]
	v_exp_f32_e32 v173, v70
	v_exp_f32_e32 v172, v86
	v_exp_f32_e32 v174, v87
	v_exp_f32_e32 v175, v71
	v_add_f32_e32 v69, v172, v173
	v_add_f32_e32 v68, v69, v68
	v_mfma_f32_32x32x16_bf16 v[52:67], v[168:171], v[108:111], v[52:67]
	v_add_f32_e32 v69, v174, v175
	v_add_f32_e32 v168, v69, v68
	v_exp_f32_e32 v71, v88
	v_exp_f32_e32 v85, v72
	v_exp_f32_e32 v70, v89
	v_exp_f32_e32 v84, v73
	v_exp_f32_e32 v73, v90
	v_exp_f32_e32 v87, v74
	v_exp_f32_e32 v72, v91
	v_exp_f32_e32 v86, v75
	v_pk_add_f32 v[68:69], v[70:71], v[84:85]
	v_mfma_f32_32x32x16_bf16 v[36:51], v[140:143], v[108:111], v[36:51]
	v_add_f32_e32 v69, v69, v168
	v_add_f32_e32 v74, v68, v69
	v_add_f32_e64 v68, v72, v86
	v_add_f32_e64 v69, v73, v87
	ds_read_b128 v[132:135], v209
	ds_read_b128 v[128:131], v209 offset:32
	ds_read_b128 v[136:139], v209 offset:6656
	ds_read_b128 v[124:127], v209 offset:64
	v_add_f32_e32 v69, v69, v74
	v_add_f32_e32 v168, v68, v69
	v_exp_f32_e32 v75, v92
	v_exp_f32_e32 v89, v76
	v_exp_f32_e32 v74, v93
	v_exp_f32_e32 v88, v77
	v_exp_f32_e32 v77, v94
	s_waitcnt lgkmcnt(12)
	v_mfma_f32_32x32x16_bf16 v[36:51], v[220:223], v[112:115], v[36:51]
	v_exp_f32_e32 v91, v78
	v_exp_f32_e32 v76, v95
	v_exp_f32_e32 v90, v79
	v_pk_add_f32 v[68:69], v[74:75], v[88:89]
	ds_read_b128 v[144:147], v209 offset:6688
	ds_read_b128 v[140:143], v209 offset:6720
	v_mfma_f32_32x32x16_bf16 v[52:67], v[212:215], v[112:115], v[52:67]
	v_add_f32_e32 v69, v69, v168
	v_add_f32_e32 v78, v68, v69
	v_add_f32_e64 v68, v76, v90
	v_add_f32_e64 v69, v77, v91
	v_add_f32_e32 v69, v69, v78
	v_add_f32_e32 v168, v68, v69
	v_mfma_f32_32x32x16_bf16 v[36:51], v[228:231], v[116:119], v[36:51]
	v_exp_f32_e32 v79, v96
	v_exp_f32_e32 v93, v80
	v_exp_f32_e32 v78, v97
	v_exp_f32_e32 v92, v81
	v_mfma_f32_32x32x16_bf16 v[52:67], v[216:219], v[116:119], v[52:67]
	v_exp_f32_e32 v95, v98
	v_exp_f32_e32 v97, v82
	v_exp_f32_e32 v94, v99
	v_mfma_f32_32x32x16_bf16 v[36:51], v[238:241], v[120:123], v[36:51]
	v_exp_f32_e32 v96, v83
	v_pk_add_f32 v[68:69], v[78:79], v[92:93]
	s_nop 0
	v_add_f32_e32 v69, v69, v168
	v_add_f32_e32 v80, v68, v69
	v_pk_add_f32 v[68:69], v[94:95], v[96:97]
	v_mfma_f32_32x32x16_bf16 v[52:67], v[224:227], v[120:123], v[52:67]
	v_add_f32_e32 v69, v69, v80
	v_add_f32_e32 v68, v68, v69
	v_add_f32_e32 v209, v2, v68
	v_cvt_pk_bf16_f32 v68, v211, v233
	v_cvt_pk_bf16_f32 v69, v172, v174
	v_cvt_pk_bf16_f32 v70, v71, v70
	v_cvt_pk_bf16_f32 v71, v73, v72
	v_cvt_pk_bf16_f32 v80, v75, v74
	v_cvt_pk_bf16_f32 v81, v77, v76
	s_waitcnt lgkmcnt(10)
	v_mfma_f32_32x32x16_bf16 v[4:19], v[68:71], v[184:187], v[4:19]
	v_cvt_pk_bf16_f32 v82, v79, v78
	v_cvt_pk_bf16_f32 v83, v95, v94
	v_cvt_pk_bf16_f32 v76, v232, v235
	v_cvt_pk_bf16_f32 v77, v173, v175
	v_mfma_f32_32x32x16_bf16 v[20:35], v[68:71], v[160:163], v[20:35]
	v_cvt_pk_bf16_f32 v78, v85, v84
	v_cvt_pk_bf16_f32 v79, v87, v86
	v_cvt_pk_bf16_f32 v72, v89, v88
	v_cvt_pk_bf16_f32 v73, v91, v90
	v_mfma_f32_32x32x16_bf16 v[4:19], v[80:83], v[180:183], v[4:19]
	v_cvt_pk_bf16_f32 v74, v93, v92
	v_cvt_pk_bf16_f32 v75, v97, v96
	s_cmp_ge_u32 s42, s36
	s_cbranch_scc1 .Lattn_exit
	s_mov_b32 s14, s41
	s_mov_b32 s15, s38
	s_mov_b32 s41, s45
	s_mov_b32 s38, s44
	s_mov_b32 s44, s40
	s_mov_b32 s40, s43
	s_mov_b32 s46, s42
	s_add_i32 s42, s46, 4
	s_min_u32 s43, s42, s37
	s_add_i32 s42, s46, 2
	s_min_u32 s45, s42, s37
	s_mulk_i32 s43, 0x3000
	s_add_u32 s48, s10, s43
	s_addc_u32 s49, s11, 0
	s_lshl_b32 s43, s45, 13
	s_add_u32 s50, s12, s43
	s_addc_u32 s51, s13, 0
	s_add_i32 m0, s22, s38
	s_and_b64 s[52:53], s[4:5], exec
	s_waitcnt vmcnt(3) lgkmcnt(0)
	s_barrier
	s_branch .LBB0_999
